# combo k=2 bswap4 + nsa/sgu epilogue loads batched, per-group store waits removed
# speedup vs baseline: 1.0084x; 1.0084x over previous
; DI float lo16(unsigned w) { return __uint_as_float(w << 16); }
; DI float hi16(unsigned w) { return __uint_as_float(w & 0xffff0000u); }
; DI float siluf_(float x) { return x / (1.f + __expf(-x)); }
; DI void nsa_item(const Params& p, int it, char* lds) {
;     ...
; #pragma unroll
;   for (int r = 0; r < 16; ++r) { ya[0][r] = yst[r * 256 + tid]; ya[1][r] = yst[(16 + r) * 256 + tid]; }
;   lsum += __shfl_xor(lsum, 32, 64);
;   const float il = g1 / lsum;
;   const u16* ow = (const u16*)(ws_ + OFF_OWIN);
;   u16* y = (u16*)(ws_ + OFF_XB);
; #pragma unroll
;   for (int db = 0; db < 2; ++db)
; #pragma unroll
;     for (int g = 0; g < 4; ++g) {
;       const int col = h * 64 + 32 * db + 8 * g + 4 * hi;
;       const u32x2 w = *(const u32x2*)(ow + tok * 256 + col), az = *(const u32x2*)(proj + tok * NP + C_AZ + col);
;       const float v0 = (ya[db][4 * g] + o[db][4 * g] * il + g2 * lo16(w[0])) * siluf_(lo16(az[0]));
;       const float v1 = (ya[db][4 * g + 1] + o[db][4 * g + 1] * il + g2 * hi16(w[0])) * siluf_(hi16(az[0]));
;       const float v2 = (ya[db][4 * g + 2] + o[db][4 * g + 2] * il + g2 * lo16(w[1])) * siluf_(lo16(az[1]));
;       const float v3 = (ya[db][4 * g + 3] + o[db][4 * g + 3] * il + g2 * hi16(w[1])) * siluf_(hi16(az[1]));
;       u32x2 v; v[0] = pk2(v0, v1); v[1] = pk2(v2, v3);
;       *(u32x2*)(y + tok * 1024 + col) = v;
;     }
.LBB0_405:
	v_lshlrev_b32_e32 v32, 16, v155
	v_mul_f32_e32 v32, 0xbfb8aa3b, v32
	v_exp_f32_e32 v32, v32
	ds_bpermute_b32 v181, v158, v151
	v_mov_b32_e32 v147, v179
	v_lshlrev_b64 v[72:73], 11, v[146:147]
	v_add_f32_e32 v32, 1.0, v32
	v_readlane_b32 s13, v234, 36
	v_readlane_b32 s12, v234, 33
	v_readlane_b32 s14, v234, 37
	v_rcp_f32_e32 v32, v32
	s_nop 0
	v_lshlrev_b32_e32 v33, 16, v154
	v_mul_f32_e32 v33, 0xbfb8aa3b, v33
	v_exp_f32_e32 v150, v33
	ds_read2st64_b32 v[70:71], v161 offset0:144 offset1:148
	ds_read2st64_b32 v[54:55], v161 offset0:208 offset1:212
	ds_read2st64_b32 v[68:69], v161 offset0:152 offset1:156
	ds_read2st64_b32 v[52:53], v161 offset0:216 offset1:220
	ds_read2st64_b32 v[66:67], v161 offset0:160 offset1:164
	ds_read2st64_b32 v[50:51], v161 offset0:224 offset1:228
	ds_read2st64_b32 v[64:65], v161 offset0:168 offset1:172
	ds_read2st64_b32 v[48:49], v161 offset0:232 offset1:236
	ds_read2st64_b32 v[62:63], v161 offset0:176 offset1:180
	ds_read2st64_b32 v[46:47], v161 offset0:240 offset1:244
	ds_read2st64_b32 v[60:61], v161 offset0:184 offset1:188
	ds_read2st64_b32 v[44:45], v161 offset0:248 offset1:252
	ds_read2st64_b32 v[58:59], v161 offset0:192 offset1:196
	ds_read_b32 v38, v162
	ds_read_b32 v39, v163
	ds_read2st64_b32 v[56:57], v161 offset0:200 offset1:204
	ds_read_b32 v34, v164
	ds_read_b32 v35, v165
	s_waitcnt lgkmcnt(14)
	v_pk_add_f32 v[36:37], v[150:151], v[180:181]
	s_nop 0
	s_nop 0
	v_rcp_f32_e32 v33, v36
	s_nop 0
	v_readlane_b32 s0, v234, 38
	v_readlane_b32 s1, v234, 39
	v_or_b32_e32 v40, v156, v148
	v_lshlrev_b64 v[42:43], 9, v[146:147]
	v_ashrrev_i32_e32 v41, 31, v40
	v_lshl_add_u64 v[42:43], s[0:1], 0, v[42:43]
	v_lshlrev_b64 v[74:75], 1, v[40:41]
	v_lshl_add_u64 v[72:73], s[0:1], 0, v[72:73]
	v_lshl_add_u64 v[40:41], v[42:43], 0, v[74:75]
	s_mov_b64 s[0:1], 0xb390000
	v_lshl_add_u64 v[42:43], v[40:41], 0, s[0:1]
	s_mov_b32 s0, 0xb390000
	v_add_co_u32_e32 v40, vcc, s0, v40
	v_rcp_f32_e32 v36, v37
	s_nop 0
	v_mul_f32_e32 v36, v33, v36
	s_nop 0
	v_addc_co_u32_e32 v41, vcc, 0, v41, vcc
	global_load_dwordx2 v[76:77], v[40:41], off
	v_lshl_add_u64 v[40:41], v[144:145], 0, v[74:75]
	global_load_dwordx2 v[78:79], v[40:41], off offset:1280
	global_load_dwordx2 v[202:203], v[42:43], off offset:16
	global_load_dwordx2 v[204:205], v[40:41], off offset:1296
	global_load_dwordx2 v[206:207], v[42:43], off offset:32
	global_load_dwordx2 v[208:209], v[40:41], off offset:1312
	global_load_dwordx2 v[210:211], v[42:43], off offset:48
	global_load_dwordx2 v[212:213], v[40:41], off offset:1328
	global_load_dwordx2 v[214:215], v[42:43], off offset:64
	global_load_dwordx2 v[216:217], v[40:41], off offset:1344
	global_load_dwordx2 v[218:219], v[42:43], off offset:80
	global_load_dwordx2 v[220:221], v[40:41], off offset:1360
	global_load_dwordx2 v[222:223], v[42:43], off offset:96
	global_load_dwordx2 v[224:225], v[40:41], off offset:1376
	global_load_dwordx2 v[226:227], v[42:43], off offset:112
	global_load_dwordx2 v[228:229], v[40:41], off offset:1392
	s_waitcnt vmcnt(0)
	v_and_b32_e32 v37, 0xffff0000, v78
	v_lshlrev_b32_e32 v33, 16, v78
	v_pk_fma_f32 v[16:17], v[16:17], v[36:37], v[70:71] op_sel_hi:[1,0,1]
	v_lshlrev_b32_e32 v70, 16, v76
	v_and_b32_e32 v71, 0xffff0000, v76
	v_mul_f32_e32 v78, 0xbfb8aa3b, v33
	v_pk_fma_f32 v[16:17], v[32:33], v[70:71], v[16:17] op_sel_hi:[0,1,1]
	v_mul_f32_e32 v70, 0xbfb8aa3b, v37
	v_exp_f32_e32 v80, v78
	v_exp_f32_e32 v81, v70
	s_nop 0
	v_pk_add_f32 v[70:71], v[80:81], 1.0 op_sel_hi:[1,0]
	s_nop 0
	s_nop 0
	v_rcp_f32_e32 v71, v71
	s_nop 0
	v_mul_f32_e32 v71, v37, v71
	s_nop 0
	v_rcp_f32_e32 v70, v70
	s_nop 0
	v_mul_f32_e32 v70, v33, v70
	v_and_b32_e32 v37, 0xffff0000, v79
	v_lshlrev_b32_e32 v33, 16, v79
	v_pk_fma_f32 v[18:19], v[18:19], v[36:37], v[68:69] op_sel_hi:[1,0,1]
	v_lshlrev_b32_e32 v68, 16, v77
	v_and_b32_e32 v69, 0xffff0000, v77
	v_pk_mul_f32 v[16:17], v[16:17], v[70:71]
	v_mul_f32_e32 v70, 0xbfb8aa3b, v33
	v_pk_fma_f32 v[18:19], v[32:33], v[68:69], v[18:19] op_sel_hi:[0,1,1]
	v_mul_f32_e32 v68, 0xbfb8aa3b, v37
	v_exp_f32_e32 v70, v70
	v_exp_f32_e32 v71, v68
	s_nop 0
	v_pk_add_f32 v[68:69], v[70:71], 1.0 op_sel_hi:[1,0]
	s_nop 0
	s_nop 0
	v_rcp_f32_e32 v69, v69
	s_nop 0
	v_mul_f32_e32 v69, v37, v69
	s_mov_b64 s[0:1], 0x2a40000
	v_rcp_f32_e32 v68, v68
	s_nop 0
	v_mul_f32_e32 v68, v33, v68
	v_pk_mul_f32 v[18:19], v[18:19], v[68:69]
	v_cvt_pk_bf16_f32 v68, v16, v17
	v_cvt_pk_bf16_f32 v69, v18, v19
	v_lshl_add_u64 v[18:19], v[72:73], 0, v[74:75]
	v_lshl_add_u64 v[16:17], v[18:19], 0, s[0:1]
	v_add_co_u32_e32 v18, vcc, s74, v18
	s_nop 1
	v_addc_co_u32_e32 v19, vcc, 0, v19, vcc
	global_store_dwordx2 v[18:19], v[68:69], off
	v_mov_b32_e32 v18, v202
	v_mov_b32_e32 v19, v203
	s_nop 0
	v_mov_b32_e32 v68, v204
	v_mov_b32_e32 v69, v205
	v_lshlrev_b32_e32 v33, 16, v68
	v_and_b32_e32 v37, 0xffff0000, v68
	v_mul_f32_e32 v68, 0xbfb8aa3b, v33
	s_waitcnt lgkmcnt(13)
	v_pk_fma_f32 v[20:21], v[20:21], v[36:37], v[66:67] op_sel_hi:[1,0,1]
	v_lshlrev_b32_e32 v66, 16, v18
	v_and_b32_e32 v67, 0xffff0000, v18
	v_mul_f32_e32 v18, 0xbfb8aa3b, v37
	v_exp_f32_e32 v70, v68
	v_exp_f32_e32 v71, v18
	v_pk_fma_f32 v[20:21], v[32:33], v[66:67], v[20:21] op_sel_hi:[0,1,1]
	v_pk_add_f32 v[66:67], v[70:71], 1.0 op_sel_hi:[1,0]
	s_nop 0
	s_nop 0
	v_rcp_f32_e32 v67, v67
	s_nop 0
	v_mul_f32_e32 v67, v37, v67
	s_nop 0
	v_rcp_f32_e32 v66, v66
	s_nop 0
	v_mul_f32_e32 v66, v33, v66
	v_lshlrev_b32_e32 v33, 16, v69
	v_and_b32_e32 v37, 0xffff0000, v69
	v_mul_f32_e32 v18, 0xbfb8aa3b, v33
	s_waitcnt lgkmcnt(11)
; DI float lo16(unsigned w) { return __uint_as_float(w << 16); }
; DI float hi16(unsigned w) { return __uint_as_float(w & 0xffff0000u); }
; DI float siluf_(float x) { return x / (1.f + __expf(-x)); }
; DI void nsa_item(const Params& p, int it, char* lds) {
;     ...
; #pragma unroll
;   for (int db = 0; db < 2; ++db)
; #pragma unroll
;     for (int g = 0; g < 4; ++g) {
;       const int col = h * 64 + 32 * db + 8 * g + 4 * hi;
;       const u32x2 w = *(const u32x2*)(ow + tok * 256 + col), az = *(const u32x2*)(proj + tok * NP + C_AZ + col);
;       const float v0 = (ya[db][4 * g] + o[db][4 * g] * il + g2 * lo16(w[0])) * siluf_(lo16(az[0]));
;       const float v1 = (ya[db][4 * g + 1] + o[db][4 * g + 1] * il + g2 * hi16(w[0])) * siluf_(hi16(az[0]));
;       const float v2 = (ya[db][4 * g + 2] + o[db][4 * g + 2] * il + g2 * lo16(w[1])) * siluf_(lo16(az[1]));
;       const float v3 = (ya[db][4 * g + 3] + o[db][4 * g + 3] * il + g2 * hi16(w[1])) * siluf_(hi16(az[1]));
;       u32x2 v; v[0] = pk2(v0, v1); v[1] = pk2(v2, v3);
;       *(u32x2*)(y + tok * 1024 + col) = v;
;     }
	v_pk_fma_f32 v[22:23], v[22:23], v[36:37], v[64:65] op_sel_hi:[1,0,1]
	v_lshlrev_b32_e32 v64, 16, v19
	v_and_b32_e32 v65, 0xffff0000, v19
	v_mul_f32_e32 v19, 0xbfb8aa3b, v37
	v_exp_f32_e32 v18, v18
	v_exp_f32_e32 v19, v19
	v_pk_fma_f32 v[22:23], v[32:33], v[64:65], v[22:23] op_sel_hi:[0,1,1]
	v_pk_mul_f32 v[20:21], v[20:21], v[66:67]
	v_pk_add_f32 v[18:19], v[18:19], 1.0 op_sel_hi:[1,0]
	s_nop 0
	v_cvt_pk_bf16_f32 v20, v20, v21
	v_rcp_f32_e32 v19, v19
	s_nop 0
	v_mul_f32_e32 v19, v37, v19
	v_div_scale_f32 v37, s[0:1], v18, v18, v33
	v_rcp_f32_e32 v64, v37
	s_nop 0
	v_fma_f32 v65, -v37, v64, 1.0
	v_fmac_f32_e32 v64, v65, v64
	v_div_scale_f32 v65, vcc, v33, v18, v33
	v_mul_f32_e32 v66, v65, v64
	v_fma_f32 v67, -v37, v66, v65
	v_fmac_f32_e32 v66, v67, v64
	v_fma_f32 v37, -v37, v66, v65
	v_div_fmas_f32 v37, v37, v64, v66
	v_div_fixup_f32 v18, v37, v18, v33
	v_pk_mul_f32 v[18:19], v[22:23], v[18:19]
	s_waitcnt lgkmcnt(9)
	v_pk_fma_f32 v[24:25], v[24:25], v[36:37], v[62:63] op_sel_hi:[1,0,1]
	v_cvt_pk_bf16_f32 v21, v18, v19
	global_store_dwordx2 v[16:17], v[20:21], off offset:16
	v_mov_b32_e32 v18, v206
	v_mov_b32_e32 v19, v207
	s_nop 0
	v_mov_b32_e32 v20, v208
	v_mov_b32_e32 v21, v209
	v_lshlrev_b32_e32 v62, 16, v18
	v_lshlrev_b32_e32 v33, 16, v20
	v_and_b32_e32 v20, 0xffff0000, v20
	v_mul_f32_e32 v22, 0xbfb8aa3b, v33
	v_and_b32_e32 v63, 0xffff0000, v18
	v_mul_f32_e32 v18, 0xbfb8aa3b, v20
	v_exp_f32_e32 v22, v22
	v_exp_f32_e32 v23, v18
	v_pk_fma_f32 v[24:25], v[32:33], v[62:63], v[24:25] op_sel_hi:[0,1,1]
	v_pk_add_f32 v[22:23], v[22:23], 1.0 op_sel_hi:[1,0]
	s_nop 0
	s_nop 0
	v_rcp_f32_e32 v23, v23
	s_nop 0
	v_mul_f32_e32 v23, v20, v23
	s_nop 0
	v_rcp_f32_e32 v22, v22
	s_nop 0
	v_mul_f32_e32 v22, v33, v22
	v_lshlrev_b32_e32 v33, 16, v21
	v_and_b32_e32 v37, 0xffff0000, v21
	v_pk_mul_f32 v[22:23], v[24:25], v[22:23]
	v_mul_f32_e32 v18, 0xbfb8aa3b, v33
	v_lshlrev_b32_e32 v24, 16, v19
	v_and_b32_e32 v25, 0xffff0000, v19
	v_mul_f32_e32 v19, 0xbfb8aa3b, v37
	v_exp_f32_e32 v18, v18
	v_exp_f32_e32 v19, v19
	s_waitcnt lgkmcnt(7)
	v_pk_fma_f32 v[20:21], v[26:27], v[36:37], v[60:61] op_sel_hi:[1,0,1]
	v_pk_add_f32 v[18:19], v[18:19], 1.0 op_sel_hi:[1,0]
	v_pk_fma_f32 v[20:21], v[32:33], v[24:25], v[20:21] op_sel_hi:[0,1,1]
	s_nop 0
	v_rcp_f32_e32 v19, v19
	s_nop 0
	v_mul_f32_e32 v19, v37, v19
	v_div_scale_f32 v24, s[0:1], v18, v18, v33
	v_rcp_f32_e32 v25, v24
	s_nop 0
	v_fma_f32 v26, -v24, v25, 1.0
	v_fmac_f32_e32 v25, v26, v25
	v_div_scale_f32 v26, vcc, v33, v18, v33
	v_mul_f32_e32 v27, v26, v25
	v_fma_f32 v37, -v24, v27, v26
	v_fmac_f32_e32 v27, v37, v25
	v_fma_f32 v24, -v24, v27, v26
	v_div_fmas_f32 v24, v24, v25, v27
	v_div_fixup_f32 v18, v24, v18, v33
	v_pk_mul_f32 v[18:19], v[20:21], v[18:19]
	v_cvt_pk_bf16_f32 v20, v22, v23
	v_cvt_pk_bf16_f32 v21, v18, v19
	global_store_dwordx2 v[16:17], v[20:21], off offset:32
	v_mov_b32_e32 v18, v210
	v_mov_b32_e32 v19, v211
	s_nop 0
	v_mov_b32_e32 v20, v212
	v_mov_b32_e32 v21, v213
	s_waitcnt lgkmcnt(5)
	v_pk_fma_f32 v[24:25], v[28:29], v[36:37], v[58:59] op_sel_hi:[1,0,1]
	v_pk_fma_f32 v[0:1], v[0:1], v[36:37], v[54:55] op_sel_hi:[1,0,1]
	v_pk_fma_f32 v[2:3], v[2:3], v[36:37], v[52:53] op_sel_hi:[1,0,1]
	v_pk_fma_f32 v[4:5], v[4:5], v[36:37], v[50:51] op_sel_hi:[1,0,1]
	v_lshlrev_b32_e32 v26, 16, v18
	v_lshlrev_b32_e32 v33, 16, v20
	v_and_b32_e32 v20, 0xffff0000, v20
	v_mul_f32_e32 v22, 0xbfb8aa3b, v33
	v_and_b32_e32 v27, 0xffff0000, v18
	v_mul_f32_e32 v18, 0xbfb8aa3b, v20
	v_exp_f32_e32 v22, v22
	v_exp_f32_e32 v23, v18
	v_pk_fma_f32 v[24:25], v[32:33], v[26:27], v[24:25] op_sel_hi:[0,1,1]
	v_pk_add_f32 v[22:23], v[22:23], 1.0 op_sel_hi:[1,0]
	s_nop 0
	s_nop 0
	v_rcp_f32_e32 v23, v23
	s_nop 0
	v_mul_f32_e32 v23, v20, v23
	s_nop 0
	v_rcp_f32_e32 v22, v22
	s_nop 0
	v_mul_f32_e32 v22, v33, v22
	v_lshlrev_b32_e32 v26, 16, v21
	v_and_b32_e32 v27, 0xffff0000, v21
	v_pk_mul_f32 v[22:23], v[24:25], v[22:23]
	v_mul_f32_e32 v18, 0xbfb8aa3b, v26
	v_lshlrev_b32_e32 v24, 16, v19
	v_and_b32_e32 v25, 0xffff0000, v19
	v_mul_f32_e32 v19, 0xbfb8aa3b, v27
	v_exp_f32_e32 v18, v18
	v_exp_f32_e32 v19, v19
	s_waitcnt lgkmcnt(2)
; DI float lo16(unsigned w) { return __uint_as_float(w << 16); }
; DI float hi16(unsigned w) { return __uint_as_float(w & 0xffff0000u); }
; DI float siluf_(float x) { return x / (1.f + __expf(-x)); }
; DI void nsa_item(const Params& p, int it, char* lds) {
;     ...
; #pragma unroll
;   for (int db = 0; db < 2; ++db)
; #pragma unroll
;     for (int g = 0; g < 4; ++g) {
;       const int col = h * 64 + 32 * db + 8 * g + 4 * hi;
;       const u32x2 w = *(const u32x2*)(ow + tok * 256 + col), az = *(const u32x2*)(proj + tok * NP + C_AZ + col);
;       const float v0 = (ya[db][4 * g] + o[db][4 * g] * il + g2 * lo16(w[0])) * siluf_(lo16(az[0]));
;       const float v1 = (ya[db][4 * g + 1] + o[db][4 * g + 1] * il + g2 * hi16(w[0])) * siluf_(hi16(az[0]));
;       const float v2 = (ya[db][4 * g + 2] + o[db][4 * g + 2] * il + g2 * lo16(w[1])) * siluf_(lo16(az[1]));
;       const float v3 = (ya[db][4 * g + 3] + o[db][4 * g + 3] * il + g2 * hi16(w[1])) * siluf_(hi16(az[1]));
;       u32x2 v; v[0] = pk2(v0, v1); v[1] = pk2(v2, v3);
;       *(u32x2*)(y + tok * 1024 + col) = v;
;     }
; __global__ void __launch_bounds__(256, 2) hybrid_megakernel(Params p) {
;     ...
;       const int gi = vb >> 4;
;       int start = 0, mine = 0;
;       for (int g2 = 0; g2 <= gi; ++g2) {
	v_pk_fma_f32 v[20:21], v[30:31], v[36:37], v[56:57] op_sel_hi:[1,0,1]
	v_pk_add_f32 v[18:19], v[18:19], 1.0 op_sel_hi:[1,0]
	v_pk_fma_f32 v[20:21], v[32:33], v[24:25], v[20:21] op_sel_hi:[0,1,1]
	s_nop 0
	v_rcp_f32_e32 v19, v19
	s_nop 0
	v_mul_f32_e32 v19, v27, v19
	s_nop 0
	v_rcp_f32_e32 v18, v18
	s_nop 0
	v_mul_f32_e32 v18, v26, v18
	v_pk_mul_f32 v[18:19], v[20:21], v[18:19]
	v_cvt_pk_bf16_f32 v20, v22, v23
	v_cvt_pk_bf16_f32 v21, v18, v19
	global_store_dwordx2 v[16:17], v[20:21], off offset:48
	v_mov_b32_e32 v18, v214
	v_mov_b32_e32 v19, v215
	s_nop 0
	v_mov_b32_e32 v20, v216
	v_mov_b32_e32 v21, v217
	v_lshlrev_b32_e32 v24, 16, v18
	v_lshlrev_b32_e32 v26, 16, v20
	v_and_b32_e32 v20, 0xffff0000, v20
	v_mul_f32_e32 v22, 0xbfb8aa3b, v26
	v_and_b32_e32 v25, 0xffff0000, v18
	v_mul_f32_e32 v18, 0xbfb8aa3b, v20
	v_exp_f32_e32 v22, v22
	v_exp_f32_e32 v23, v18
	v_pk_fma_f32 v[0:1], v[32:33], v[24:25], v[0:1] op_sel_hi:[0,1,1]
	v_pk_add_f32 v[22:23], v[22:23], 1.0 op_sel_hi:[1,0]
	s_nop 0
	s_nop 0
	v_rcp_f32_e32 v23, v23
	s_nop 0
	v_mul_f32_e32 v23, v20, v23
	s_nop 0
	v_rcp_f32_e32 v22, v22
	s_nop 0
	v_mul_f32_e32 v22, v26, v22
	v_pk_mul_f32 v[0:1], v[0:1], v[22:23]
	v_lshlrev_b32_e32 v22, 16, v21
	v_and_b32_e32 v23, 0xffff0000, v21
	v_mul_f32_e32 v18, 0xbfb8aa3b, v22
	v_lshlrev_b32_e32 v20, 16, v19
	v_and_b32_e32 v21, 0xffff0000, v19
	v_mul_f32_e32 v19, 0xbfb8aa3b, v23
	v_exp_f32_e32 v18, v18
	v_exp_f32_e32 v19, v19
	v_pk_fma_f32 v[2:3], v[32:33], v[20:21], v[2:3] op_sel_hi:[0,1,1]
	v_cvt_pk_bf16_f32 v0, v0, v1
	v_pk_add_f32 v[18:19], v[18:19], 1.0 op_sel_hi:[1,0]
	s_nop 0
	s_nop 0
	v_rcp_f32_e32 v19, v19
	s_nop 0
	v_mul_f32_e32 v19, v23, v19
	s_nop 0
	v_rcp_f32_e32 v18, v18
	s_nop 0
	v_mul_f32_e32 v18, v22, v18
	v_pk_mul_f32 v[2:3], v[2:3], v[18:19]
	s_nop 0
	v_cvt_pk_bf16_f32 v1, v2, v3
	global_store_dwordx2 v[16:17], v[0:1], off offset:64
	v_mov_b32_e32 v0, v218
	v_mov_b32_e32 v1, v219
	s_nop 0
	v_mov_b32_e32 v2, v220
	v_mov_b32_e32 v3, v221
	v_lshlrev_b32_e32 v20, 16, v0
	v_lshlrev_b32_e32 v22, 16, v2
	v_and_b32_e32 v2, 0xffff0000, v2
	v_mul_f32_e32 v18, 0xbfb8aa3b, v22
	v_and_b32_e32 v21, 0xffff0000, v0
	v_mul_f32_e32 v0, 0xbfb8aa3b, v2
	v_exp_f32_e32 v18, v18
	v_exp_f32_e32 v19, v0
	v_pk_fma_f32 v[4:5], v[32:33], v[20:21], v[4:5] op_sel_hi:[0,1,1]
	v_pk_add_f32 v[18:19], v[18:19], 1.0 op_sel_hi:[1,0]
	s_nop 0
	s_nop 0
	v_rcp_f32_e32 v19, v19
	s_nop 0
	v_mul_f32_e32 v19, v2, v19
	s_nop 0
	v_rcp_f32_e32 v18, v18
	s_nop 0
	v_mul_f32_e32 v18, v22, v18
	v_pk_mul_f32 v[4:5], v[4:5], v[18:19]
	v_lshlrev_b32_e32 v18, 16, v3
	v_and_b32_e32 v19, 0xffff0000, v3
	v_mul_f32_e32 v0, 0xbfb8aa3b, v18
	v_pk_fma_f32 v[2:3], v[6:7], v[36:37], v[48:49] op_sel_hi:[1,0,1]
	v_lshlrev_b32_e32 v6, 16, v1
	v_and_b32_e32 v7, 0xffff0000, v1
	v_mul_f32_e32 v1, 0xbfb8aa3b, v19
	v_exp_f32_e32 v0, v0
	v_exp_f32_e32 v1, v1
	v_pk_fma_f32 v[2:3], v[32:33], v[6:7], v[2:3] op_sel_hi:[0,1,1]
	v_pk_add_f32 v[0:1], v[0:1], 1.0 op_sel_hi:[1,0]
	s_nop 0
	s_nop 0
	v_rcp_f32_e32 v1, v1
	s_nop 0
	v_mul_f32_e32 v1, v19, v1
	s_nop 0
	v_rcp_f32_e32 v0, v0
	s_nop 0
	v_mul_f32_e32 v0, v18, v0
	v_pk_mul_f32 v[0:1], v[2:3], v[0:1]
	v_cvt_pk_bf16_f32 v2, v4, v5
	v_cvt_pk_bf16_f32 v3, v0, v1
	global_store_dwordx2 v[16:17], v[2:3], off offset:80
	v_mov_b32_e32 v0, v222
	v_mov_b32_e32 v1, v223
	s_nop 0
	v_mov_b32_e32 v2, v224
	v_mov_b32_e32 v3, v225
	v_pk_fma_f32 v[6:7], v[8:9], v[36:37], v[46:47] op_sel_hi:[1,0,1]
	v_lshlrev_b32_e32 v8, 16, v0
	v_lshlrev_b32_e32 v18, 16, v2
	v_and_b32_e32 v2, 0xffff0000, v2
	v_mul_f32_e32 v4, 0xbfb8aa3b, v18
	v_and_b32_e32 v9, 0xffff0000, v0
	v_mul_f32_e32 v0, 0xbfb8aa3b, v2
	v_exp_f32_e32 v4, v4
	v_exp_f32_e32 v5, v0
	v_pk_fma_f32 v[6:7], v[32:33], v[8:9], v[6:7] op_sel_hi:[0,1,1]
	v_pk_add_f32 v[4:5], v[4:5], 1.0 op_sel_hi:[1,0]
	s_nop 0
	s_nop 0
	v_rcp_f32_e32 v5, v5
	s_nop 0
	v_mul_f32_e32 v5, v2, v5
	s_nop 0
	v_rcp_f32_e32 v4, v4
	s_nop 0
	v_mul_f32_e32 v4, v18, v4
	v_lshlrev_b32_e32 v8, 16, v3
	v_and_b32_e32 v9, 0xffff0000, v3
	v_pk_mul_f32 v[4:5], v[6:7], v[4:5]
	v_mul_f32_e32 v0, 0xbfb8aa3b, v8
	v_lshlrev_b32_e32 v6, 16, v1
	v_and_b32_e32 v7, 0xffff0000, v1
	v_mul_f32_e32 v1, 0xbfb8aa3b, v9
	v_exp_f32_e32 v0, v0
	v_exp_f32_e32 v1, v1
	v_pk_fma_f32 v[2:3], v[10:11], v[36:37], v[44:45] op_sel_hi:[1,0,1]
	v_pk_add_f32 v[0:1], v[0:1], 1.0 op_sel_hi:[1,0]
	v_pk_fma_f32 v[2:3], v[32:33], v[6:7], v[2:3] op_sel_hi:[0,1,1]
	s_nop 0
	v_rcp_f32_e32 v1, v1
	s_nop 0
	v_mul_f32_e32 v1, v9, v1
	s_nop 0
	v_rcp_f32_e32 v0, v0
	s_nop 0
	v_mul_f32_e32 v0, v8, v0
	v_pk_mul_f32 v[0:1], v[2:3], v[0:1]
	v_cvt_pk_bf16_f32 v2, v4, v5
	v_cvt_pk_bf16_f32 v3, v0, v1
	global_store_dwordx2 v[16:17], v[2:3], off offset:96
	v_mov_b32_e32 v0, v226
	v_mov_b32_e32 v1, v227
	s_nop 0
	v_mov_b32_e32 v2, v228
	v_mov_b32_e32 v3, v229
	v_pk_fma_f32 v[6:7], v[12:13], v[36:37], v[38:39] op_sel_hi:[1,0,1]
	v_lshlrev_b32_e32 v8, 16, v0
	v_lshlrev_b32_e32 v10, 16, v2
	v_and_b32_e32 v2, 0xffff0000, v2
	v_mul_f32_e32 v4, 0xbfb8aa3b, v10
	v_and_b32_e32 v9, 0xffff0000, v0
	v_mul_f32_e32 v0, 0xbfb8aa3b, v2
	v_exp_f32_e32 v4, v4
	v_exp_f32_e32 v5, v0
	v_pk_fma_f32 v[6:7], v[32:33], v[8:9], v[6:7] op_sel_hi:[0,1,1]
	v_pk_add_f32 v[4:5], v[4:5], 1.0 op_sel_hi:[1,0]
	s_nop 0
	s_nop 0
	v_rcp_f32_e32 v5, v5
	s_nop 0
	v_mul_f32_e32 v5, v2, v5
	s_nop 0
	v_rcp_f32_e32 v4, v4
	s_nop 0
	v_mul_f32_e32 v4, v10, v4
	v_lshlrev_b32_e32 v8, 16, v3
	v_and_b32_e32 v9, 0xffff0000, v3
	v_pk_mul_f32 v[4:5], v[6:7], v[4:5]
	v_mul_f32_e32 v0, 0xbfb8aa3b, v8
	v_lshlrev_b32_e32 v6, 16, v1
	v_and_b32_e32 v7, 0xffff0000, v1
	v_mul_f32_e32 v1, 0xbfb8aa3b, v9
	v_exp_f32_e32 v0, v0
	v_exp_f32_e32 v1, v1
	s_waitcnt lgkmcnt(0)
	v_pk_fma_f32 v[2:3], v[14:15], v[36:37], v[34:35] op_sel_hi:[1,0,1]
	v_pk_add_f32 v[0:1], v[0:1], 1.0 op_sel_hi:[1,0]
	v_pk_fma_f32 v[2:3], v[32:33], v[6:7], v[2:3] op_sel_hi:[0,1,1]
	s_nop 0
	v_rcp_f32_e32 v1, v1
	s_nop 0
	v_mul_f32_e32 v1, v9, v1
	s_ashr_i32 s0, s13, 4
	s_cmp_lt_i32 s0, 0
	v_rcp_f32_e32 v0, v0
	s_nop 0
	v_mul_f32_e32 v0, v8, v0
	v_pk_mul_f32 v[0:1], v[2:3], v[0:1]
	v_cvt_pk_bf16_f32 v2, v4, v5
	v_cvt_pk_bf16_f32 v3, v0, v1
	global_store_dwordx2 v[16:17], v[2:3], off offset:112
	s_cbranch_scc1 .LBB0_409
	s_add_i32 s1, s0, 1
	s_mov_b32 s2, 0
	v_mov_b32_e32 v116, 0
	v_mov_b32_e32 v0, 0

; DI float lo16(unsigned w) { return __uint_as_float(w << 16); }
; DI float hi16(unsigned w) { return __uint_as_float(w & 0xffff0000u); }
; DI float siluf_(float x) { return x / (1.f + __expf(-x)); }
; DI void sgu_item(const Params& p, int l, int it, char* lds) {
;     ...
;   const size_t tok = (size_t)b * S_ + t0 + i;
;   const float bs = p.b_sp[(l * 4 + g) * 128 + i];
;   u16* y = (u16*)(ws_ + OFF_XB);
; #pragma unroll
;   for (int ct = 0; ct < 2; ++ct)
; #pragma unroll
;     for (int g4 = 0; g4 < 4; ++g4) {
;       const int col = g * 64 + ct * 32 + 8 * g4 + 4 * hi;
;       const u32x2 u = *(const u32x2*)(proj + tok * NP + C_DU + col), z = *(const u32x2*)(proj + tok * NP + C_DZ + col);
;       u32x2 v;
;       v[0] = pk2(lo16(u[0]) * (acc[ct][4 * g4] + bs) * siluf_(lo16(z[0])), hi16(u[0]) * (acc[ct][4 * g4 + 1] + bs) * siluf_(hi16(z[0])));
;       v[1] = pk2(lo16(u[1]) * (acc[ct][4 * g4 + 2] + bs) * siluf_(lo16(z[1])), hi16(u[1]) * (acc[ct][4 * g4 + 3] + bs) * siluf_(hi16(z[1])));
;       *(u32x2*)(y + tok * 1024 + 768 + col) = v;
;     }
.LBB0_445:
	v_mov_b32_e32 v95, v179
	v_lshl_add_u64 v[32:33], v[96:97], 0, v[94:95]
	v_lshl_add_u32 v34, v99, 7, v96
	v_mov_b64_e32 v[36:37], s[2:3]
	v_ashrrev_i32_e32 v35, 31, v34
	v_mad_i64_i32 v[36:37], s[2:3], v32, s33, v[36:37]
	v_lshl_add_u64 v[34:35], v[34:35], 2, s[82:83]
	s_mov_b64 s[2:3], 0x1300
	global_load_dword v34, v[34:35], off
	v_lshl_add_u64 v[38:39], v[36:37], 0, s[2:3]
	s_mov_b64 s[2:3], 0x1700
	v_lshlrev_b32_e32 v35, 7, v93
	v_lshl_add_u64 v[36:37], v[36:37], 0, s[2:3]
	v_lshl_or_b32 v178, v98, 3, v35
	v_lshl_add_u64 v[40:41], v[38:39], 0, v[178:179]
	v_lshl_add_u64 v[42:43], v[36:37], 0, v[178:179]
	global_load_dwordx2 v[40:41], v[40:41], off
	v_lshlrev_b64 v[32:33], 11, v[32:33]
	global_load_dwordx2 v[42:43], v[42:43], off
	v_lshl_add_u64 v[100:101], v[38:39], 0, v[178:179]
	v_lshl_add_u64 v[102:103], v[36:37], 0, v[178:179]
	global_load_dwordx2 v[68:69], v[100:101], off offset:16
	global_load_dwordx2 v[70:71], v[102:103], off offset:16
	global_load_dwordx2 v[72:73], v[100:101], off offset:32
	global_load_dwordx2 v[74:75], v[102:103], off offset:32
	global_load_dwordx2 v[76:77], v[100:101], off offset:48
	global_load_dwordx2 v[78:79], v[102:103], off offset:48
	global_load_dwordx2 v[80:81], v[100:101], off offset:64
	global_load_dwordx2 v[82:83], v[102:103], off offset:64
	global_load_dwordx2 v[84:85], v[100:101], off offset:80
	global_load_dwordx2 v[86:87], v[102:103], off offset:80
	global_load_dwordx2 v[88:89], v[100:101], off offset:96
	global_load_dwordx2 v[90:91], v[102:103], off offset:96
	global_load_dwordx2 v[104:105], v[100:101], off offset:112
	global_load_dwordx2 v[106:107], v[102:103], off offset:112
	v_lshl_add_u64 v[32:33], s[0:1], 0, v[32:33]
	s_mov_b64 s[0:1], 0x2a40600
	v_lshl_add_u64 v[32:33], v[32:33], 0, s[0:1]
	v_mov_b32_e32 v121, v176
	s_waitcnt vmcnt(1)
	v_lshlrev_b32_e32 v46, 16, v40
	v_and_b32_e32 v47, 0xffff0000, v40
	s_waitcnt vmcnt(0)
	v_lshlrev_b32_e32 v35, 16, v42
	v_and_b32_e32 v42, 0xffff0000, v42
	v_mul_f32_e32 v44, 0xbfb8aa3b, v35
	v_mul_f32_e32 v40, 0xbfb8aa3b, v42
	v_exp_f32_e32 v44, v44
	v_exp_f32_e32 v45, v40
	v_pk_add_f32 v[0:1], v[34:35], v[0:1] op_sel_hi:[0,1]
	v_pk_mul_f32 v[0:1], v[0:1], v[46:47]
	v_pk_add_f32 v[44:45], v[44:45], 1.0 op_sel_hi:[1,0]
	s_nop 0
	s_nop 0
	v_rcp_f32_e32 v45, v45
	s_nop 0
	v_mul_f32_e32 v45, v42, v45
	s_nop 0
	v_rcp_f32_e32 v44, v44
	s_nop 0
	v_mul_f32_e32 v44, v35, v44
	v_pk_mul_f32 v[0:1], v[0:1], v[44:45]
	v_and_b32_e32 v35, 0xffff0000, v43
	v_cvt_pk_bf16_f32 v0, v0, v1
	v_lshlrev_b32_e32 v1, 16, v43
	v_mul_f32_e32 v40, 0xbfb8aa3b, v1
	v_lshlrev_b32_e32 v42, 16, v41
	v_and_b32_e32 v43, 0xffff0000, v41
	v_mul_f32_e32 v41, 0xbfb8aa3b, v35
	v_exp_f32_e32 v40, v40
	v_exp_f32_e32 v41, v41
	v_pk_add_f32 v[2:3], v[34:35], v[2:3] op_sel_hi:[0,1]
	v_pk_mul_f32 v[2:3], v[2:3], v[42:43]
	v_pk_add_f32 v[40:41], v[40:41], 1.0 op_sel_hi:[1,0]
	s_nop 0
	s_nop 0
	v_rcp_f32_e32 v41, v41
	s_nop 0
	v_mul_f32_e32 v41, v35, v41
	s_nop 0
	v_rcp_f32_e32 v40, v40
	s_nop 0
	v_mul_f32_e32 v40, v1, v40
	v_pk_mul_f32 v[2:3], v[2:3], v[40:41]
	s_nop 0
	v_cvt_pk_bf16_f32 v1, v2, v3
	v_lshl_add_u64 v[2:3], v[32:33], 0, v[178:179]
	global_store_dwordx2 v[2:3], v[0:1], off
	v_or_b32_e32 v0, 16, v178
	v_mov_b32_e32 v1, v179
	v_lshl_add_u64 v[2:3], v[38:39], 0, v[0:1]
	v_lshl_add_u64 v[40:41], v[36:37], 0, v[0:1]
	v_mov_b32_e32 v2, v68
	v_mov_b32_e32 v3, v69
	v_lshl_add_u64 v[0:1], v[32:33], 0, v[0:1]
	v_mov_b32_e32 v40, v70
	v_mov_b32_e32 v41, v71
	v_lshlrev_b32_e32 v44, 16, v2
	v_and_b32_e32 v45, 0xffff0000, v2
	v_lshlrev_b32_e32 v35, 16, v40
	v_and_b32_e32 v40, 0xffff0000, v40
	v_mul_f32_e32 v42, 0xbfb8aa3b, v35
	v_mul_f32_e32 v2, 0xbfb8aa3b, v40
	v_exp_f32_e32 v42, v42
	v_exp_f32_e32 v43, v2
	v_pk_add_f32 v[4:5], v[34:35], v[4:5] op_sel_hi:[0,1]
	v_pk_mul_f32 v[4:5], v[4:5], v[44:45]
	v_pk_add_f32 v[42:43], v[42:43], 1.0 op_sel_hi:[1,0]
	s_nop 0
	s_nop 0
	v_rcp_f32_e32 v43, v43
	s_nop 0
	v_mul_f32_e32 v43, v40, v43
	s_nop 0
	v_rcp_f32_e32 v42, v42
	s_nop 0
	v_mul_f32_e32 v42, v35, v42
	v_pk_mul_f32 v[4:5], v[4:5], v[42:43]
	v_lshlrev_b32_e32 v35, 16, v41
	v_and_b32_e32 v42, 0xffff0000, v41
	v_cvt_pk_bf16_f32 v2, v4, v5
	v_mul_f32_e32 v4, 0xbfb8aa3b, v35
	v_lshlrev_b32_e32 v40, 16, v3
	v_and_b32_e32 v41, 0xffff0000, v3
	v_mul_f32_e32 v3, 0xbfb8aa3b, v42
	v_exp_f32_e32 v4, v4
	v_exp_f32_e32 v5, v3
	v_pk_add_f32 v[6:7], v[34:35], v[6:7] op_sel_hi:[0,1]
	v_pk_mul_f32 v[6:7], v[6:7], v[40:41]
	v_pk_add_f32 v[4:5], v[4:5], 1.0 op_sel_hi:[1,0]
	s_nop 0
	s_nop 0
	v_rcp_f32_e32 v5, v5
	s_nop 0
	v_mul_f32_e32 v5, v42, v5
	s_nop 0
	v_rcp_f32_e32 v4, v4
	s_nop 0
	v_mul_f32_e32 v4, v35, v4
	v_pk_mul_f32 v[4:5], v[6:7], v[4:5]
	s_nop 0
	v_cvt_pk_bf16_f32 v3, v4, v5
	global_store_dwordx2 v[0:1], v[2:3], off
	v_or_b32_e32 v0, 32, v178
	v_mov_b32_e32 v1, v179
	v_lshl_add_u64 v[2:3], v[38:39], 0, v[0:1]
	v_lshl_add_u64 v[4:5], v[36:37], 0, v[0:1]
	v_mov_b32_e32 v2, v72
	v_mov_b32_e32 v3, v73
	v_lshl_add_u64 v[0:1], v[32:33], 0, v[0:1]
	v_mov_b32_e32 v4, v74
	v_mov_b32_e32 v5, v75
	v_lshlrev_b32_e32 v40, 16, v2
	v_and_b32_e32 v41, 0xffff0000, v2
	v_lshlrev_b32_e32 v35, 16, v4
	v_and_b32_e32 v4, 0xffff0000, v4
	v_mul_f32_e32 v6, 0xbfb8aa3b, v35
	v_mul_f32_e32 v2, 0xbfb8aa3b, v4
	v_exp_f32_e32 v6, v6
	v_exp_f32_e32 v7, v2
	v_pk_add_f32 v[8:9], v[34:35], v[8:9] op_sel_hi:[0,1]
	v_pk_mul_f32 v[8:9], v[8:9], v[40:41]
	v_pk_add_f32 v[6:7], v[6:7], 1.0 op_sel_hi:[1,0]
	s_nop 0
	s_nop 0
	v_rcp_f32_e32 v7, v7
	s_nop 0
	v_mul_f32_e32 v7, v4, v7
	s_nop 0
	v_rcp_f32_e32 v6, v6
	s_nop 0
	v_mul_f32_e32 v6, v35, v6
	v_pk_mul_f32 v[6:7], v[8:9], v[6:7]
	v_lshlrev_b32_e32 v35, 16, v5
	v_and_b32_e32 v40, 0xffff0000, v5
; DI float lo16(unsigned w) { return __uint_as_float(w << 16); }
; DI float hi16(unsigned w) { return __uint_as_float(w & 0xffff0000u); }
; DI float siluf_(float x) { return x / (1.f + __expf(-x)); }
; DI void sgu_item(const Params& p, int l, int it, char* lds) {
;     ...
; #pragma unroll
;   for (int ct = 0; ct < 2; ++ct)
; #pragma unroll
;     for (int g4 = 0; g4 < 4; ++g4) {
;       const int col = g * 64 + ct * 32 + 8 * g4 + 4 * hi;
;       const u32x2 u = *(const u32x2*)(proj + tok * NP + C_DU + col), z = *(const u32x2*)(proj + tok * NP + C_DZ + col);
;       u32x2 v;
;       v[0] = pk2(lo16(u[0]) * (acc[ct][4 * g4] + bs) * siluf_(lo16(z[0])), hi16(u[0]) * (acc[ct][4 * g4 + 1] + bs) * siluf_(hi16(z[0])));
;       v[1] = pk2(lo16(u[1]) * (acc[ct][4 * g4 + 2] + bs) * siluf_(lo16(z[1])), hi16(u[1]) * (acc[ct][4 * g4 + 3] + bs) * siluf_(hi16(z[1])));
;       *(u32x2*)(y + tok * 1024 + 768 + col) = v;
;     }
	v_cvt_pk_bf16_f32 v2, v6, v7
	v_mul_f32_e32 v4, 0xbfb8aa3b, v35
	v_lshlrev_b32_e32 v6, 16, v3
	v_and_b32_e32 v7, 0xffff0000, v3
	v_mul_f32_e32 v3, 0xbfb8aa3b, v40
	v_exp_f32_e32 v4, v4
	v_exp_f32_e32 v5, v3
	v_pk_add_f32 v[8:9], v[34:35], v[10:11] op_sel_hi:[0,1]
	v_pk_mul_f32 v[6:7], v[8:9], v[6:7]
	v_pk_add_f32 v[4:5], v[4:5], 1.0 op_sel_hi:[1,0]
	s_nop 0
	s_nop 0
	v_rcp_f32_e32 v5, v5
	s_nop 0
	v_mul_f32_e32 v5, v40, v5
	s_nop 0
	v_rcp_f32_e32 v4, v4
	s_nop 0
	v_mul_f32_e32 v4, v35, v4
	v_pk_mul_f32 v[4:5], v[6:7], v[4:5]
	s_nop 0
	v_cvt_pk_bf16_f32 v3, v4, v5
	global_store_dwordx2 v[0:1], v[2:3], off
	v_or_b32_e32 v0, 48, v178
	v_mov_b32_e32 v1, v179
	v_lshl_add_u64 v[2:3], v[38:39], 0, v[0:1]
	v_lshl_add_u64 v[4:5], v[36:37], 0, v[0:1]
	v_mov_b32_e32 v2, v76
	v_mov_b32_e32 v3, v77
	v_lshl_add_u64 v[0:1], v[32:33], 0, v[0:1]
	v_mov_b32_e32 v4, v78
	v_mov_b32_e32 v5, v79
	v_lshlrev_b32_e32 v8, 16, v2
	v_and_b32_e32 v9, 0xffff0000, v2
	v_lshlrev_b32_e32 v35, 16, v4
	v_and_b32_e32 v4, 0xffff0000, v4
	v_mul_f32_e32 v6, 0xbfb8aa3b, v35
	v_mul_f32_e32 v2, 0xbfb8aa3b, v4
	v_exp_f32_e32 v6, v6
	v_exp_f32_e32 v7, v2
	v_pk_add_f32 v[10:11], v[34:35], v[12:13] op_sel_hi:[0,1]
	v_pk_mul_f32 v[8:9], v[10:11], v[8:9]
	v_pk_add_f32 v[6:7], v[6:7], 1.0 op_sel_hi:[1,0]
	s_nop 0
	s_nop 0
	v_rcp_f32_e32 v7, v7
	s_nop 0
	v_mul_f32_e32 v7, v4, v7
	s_nop 0
	v_rcp_f32_e32 v6, v6
	s_nop 0
	v_mul_f32_e32 v6, v35, v6
	v_pk_mul_f32 v[6:7], v[8:9], v[6:7]
	v_lshlrev_b32_e32 v10, 16, v5
	v_and_b32_e32 v11, 0xffff0000, v5
	v_cvt_pk_bf16_f32 v2, v6, v7
	v_mul_f32_e32 v4, 0xbfb8aa3b, v10
	v_lshlrev_b32_e32 v6, 16, v3
	v_and_b32_e32 v7, 0xffff0000, v3
	v_mul_f32_e32 v3, 0xbfb8aa3b, v11
	v_exp_f32_e32 v4, v4
	v_exp_f32_e32 v5, v3
	v_pk_add_f32 v[8:9], v[34:35], v[14:15] op_sel_hi:[0,1]
	v_pk_mul_f32 v[6:7], v[8:9], v[6:7]
	v_mov_b32_e32 v15, 0
	v_pk_add_f32 v[4:5], v[4:5], 1.0 op_sel_hi:[1,0]
	s_nop 0
	s_nop 0
	v_rcp_f32_e32 v5, v5
	s_nop 0
	v_mul_f32_e32 v5, v11, v5
	s_nop 0
	v_rcp_f32_e32 v4, v4
	s_nop 0
	v_mul_f32_e32 v4, v10, v4
	v_pk_mul_f32 v[4:5], v[6:7], v[4:5]
	v_pk_add_f32 v[10:11], v[34:35], v[16:17] op_sel_hi:[0,1]
	v_cvt_pk_bf16_f32 v3, v4, v5
	global_store_dwordx2 v[0:1], v[2:3], off
	v_or_b32_e32 v0, 64, v178
	v_mov_b32_e32 v1, v179
	v_lshl_add_u64 v[2:3], v[38:39], 0, v[0:1]
	v_lshl_add_u64 v[4:5], v[36:37], 0, v[0:1]
	v_mov_b32_e32 v2, v80
	v_mov_b32_e32 v3, v81
	v_lshl_add_u64 v[0:1], v[32:33], 0, v[0:1]
	v_mov_b32_e32 v4, v82
	v_mov_b32_e32 v5, v83
	v_lshlrev_b32_e32 v8, 16, v2
	v_and_b32_e32 v9, 0xffff0000, v2
	v_lshlrev_b32_e32 v12, 16, v4
	v_and_b32_e32 v4, 0xffff0000, v4
	v_mul_f32_e32 v6, 0xbfb8aa3b, v12
	v_mul_f32_e32 v2, 0xbfb8aa3b, v4
	v_exp_f32_e32 v6, v6
	v_exp_f32_e32 v7, v2
	v_pk_mul_f32 v[8:9], v[10:11], v[8:9]
	v_pk_add_f32 v[6:7], v[6:7], 1.0 op_sel_hi:[1,0]
	s_nop 0
	s_nop 0
	v_rcp_f32_e32 v7, v7
	s_nop 0
	v_mul_f32_e32 v7, v4, v7
	s_nop 0
	v_rcp_f32_e32 v6, v6
	s_nop 0
	v_mul_f32_e32 v6, v12, v6
	v_pk_mul_f32 v[6:7], v[8:9], v[6:7]
	v_lshlrev_b32_e32 v10, 16, v5
	v_and_b32_e32 v11, 0xffff0000, v5
	v_cvt_pk_bf16_f32 v2, v6, v7
	v_mul_f32_e32 v4, 0xbfb8aa3b, v10
	v_lshlrev_b32_e32 v6, 16, v3
	v_and_b32_e32 v7, 0xffff0000, v3
	v_mul_f32_e32 v3, 0xbfb8aa3b, v11
	v_exp_f32_e32 v4, v4
	v_exp_f32_e32 v5, v3
	v_pk_add_f32 v[8:9], v[34:35], v[18:19] op_sel_hi:[0,1]
	v_pk_mul_f32 v[6:7], v[8:9], v[6:7]
	v_pk_add_f32 v[4:5], v[4:5], 1.0 op_sel_hi:[1,0]
	s_nop 0
	s_nop 0
	v_rcp_f32_e32 v5, v5
	s_nop 0
	v_mul_f32_e32 v5, v11, v5
	s_nop 0
	v_rcp_f32_e32 v4, v4
	s_nop 0
	v_mul_f32_e32 v4, v10, v4
	v_pk_mul_f32 v[4:5], v[6:7], v[4:5]
	v_pk_add_f32 v[10:11], v[34:35], v[20:21] op_sel_hi:[0,1]
	v_cvt_pk_bf16_f32 v3, v4, v5
	global_store_dwordx2 v[0:1], v[2:3], off
	v_or_b32_e32 v0, 0x50, v178
	v_mov_b32_e32 v1, v179
	v_lshl_add_u64 v[2:3], v[38:39], 0, v[0:1]
	v_lshl_add_u64 v[4:5], v[36:37], 0, v[0:1]
	v_mov_b32_e32 v2, v84
	v_mov_b32_e32 v3, v85
	v_lshl_add_u64 v[0:1], v[32:33], 0, v[0:1]
	v_mov_b32_e32 v4, v86
	v_mov_b32_e32 v5, v87
	v_lshlrev_b32_e32 v8, 16, v2
	v_and_b32_e32 v9, 0xffff0000, v2
	v_lshlrev_b32_e32 v12, 16, v4
	v_and_b32_e32 v4, 0xffff0000, v4
	v_mul_f32_e32 v6, 0xbfb8aa3b, v12
	v_mul_f32_e32 v2, 0xbfb8aa3b, v4
	v_exp_f32_e32 v6, v6
	v_exp_f32_e32 v7, v2
	v_pk_mul_f32 v[8:9], v[10:11], v[8:9]
	v_pk_add_f32 v[6:7], v[6:7], 1.0 op_sel_hi:[1,0]
	s_nop 0
	s_nop 0
	v_rcp_f32_e32 v7, v7
	s_nop 0
	v_mul_f32_e32 v7, v4, v7
	s_nop 0
; DI int tidx() { int t = threadIdx.x; asm volatile("" : "+v"(t)); return t; }
; DI float lo16(unsigned w) { return __uint_as_float(w << 16); }
; DI float hi16(unsigned w) { return __uint_as_float(w & 0xffff0000u); }
; DI float siluf_(float x) { return x / (1.f + __expf(-x)); }
; DI void pool_item(const Params& p, int l, int it, char* lds) {
;     ...
;   const int b = it & 7, qt = it >> 3, q0 = qt * 32;
;   const int tid = tidx(), lane = tid & 63, g = tid >> 6, l31 = lane & 31, hi = lane >> 5;
;   const u16* proj = (const u16*)(ws_ + OFF_PROJ);
;   u16* cin = (u16*)lds;
;   char* pl = lds + 48 * 512;
;   u32x4 cv[6];
; #pragma unroll
;   for (int i = 0; i < 6; ++i) {
;     const int c = tid + 256 * i, row = c >> 5, ch = c & 31; const int t = q0 - 16 + row;
;     cv[i] = u32x4{0u, 0u, 0u, 0u};
;     if (t >= 0) cv[i] = *(const u32x4*)(proj + ((size_t)b * S_ + t) * NP + C_CIN + ch * 8);
; DI void sgu_item(const Params& p, int l, int it, char* lds) {
;     ...
; #pragma unroll
;   for (int ct = 0; ct < 2; ++ct)
; #pragma unroll
;     for (int g4 = 0; g4 < 4; ++g4) {
;       const int col = g * 64 + ct * 32 + 8 * g4 + 4 * hi;
;       const u32x2 u = *(const u32x2*)(proj + tok * NP + C_DU + col), z = *(const u32x2*)(proj + tok * NP + C_DZ + col);
;       u32x2 v;
;       v[0] = pk2(lo16(u[0]) * (acc[ct][4 * g4] + bs) * siluf_(lo16(z[0])), hi16(u[0]) * (acc[ct][4 * g4 + 1] + bs) * siluf_(hi16(z[0])));
;       v[1] = pk2(lo16(u[1]) * (acc[ct][4 * g4 + 2] + bs) * siluf_(lo16(z[1])), hi16(u[1]) * (acc[ct][4 * g4 + 3] + bs) * siluf_(hi16(z[1])));
;       *(u32x2*)(y + tok * 1024 + 768 + col) = v;
;     }
	v_rcp_f32_e32 v6, v6
	s_nop 0
	v_mul_f32_e32 v6, v12, v6
	v_pk_mul_f32 v[6:7], v[8:9], v[6:7]
	v_lshlrev_b32_e32 v10, 16, v5
	v_and_b32_e32 v11, 0xffff0000, v5
	v_cvt_pk_bf16_f32 v2, v6, v7
	v_mul_f32_e32 v4, 0xbfb8aa3b, v10
	v_lshlrev_b32_e32 v6, 16, v3
	v_and_b32_e32 v7, 0xffff0000, v3
	v_mul_f32_e32 v3, 0xbfb8aa3b, v11
	v_exp_f32_e32 v4, v4
	v_exp_f32_e32 v5, v3
	v_pk_add_f32 v[8:9], v[34:35], v[22:23] op_sel_hi:[0,1]
	v_pk_mul_f32 v[6:7], v[8:9], v[6:7]
	v_pk_add_f32 v[4:5], v[4:5], 1.0 op_sel_hi:[1,0]
	s_nop 0
	s_nop 0
	v_rcp_f32_e32 v5, v5
	s_nop 0
	v_mul_f32_e32 v5, v11, v5
	s_nop 0
	v_rcp_f32_e32 v4, v4
	s_nop 0
	v_mul_f32_e32 v4, v10, v4
	v_pk_mul_f32 v[4:5], v[6:7], v[4:5]
	v_pk_add_f32 v[10:11], v[34:35], v[24:25] op_sel_hi:[0,1]
	v_cvt_pk_bf16_f32 v3, v4, v5
	global_store_dwordx2 v[0:1], v[2:3], off
	v_or_b32_e32 v0, 0x60, v178
	v_mov_b32_e32 v1, v179
	v_lshl_add_u64 v[2:3], v[38:39], 0, v[0:1]
	v_lshl_add_u64 v[4:5], v[36:37], 0, v[0:1]
	v_mov_b32_e32 v2, v88
	v_mov_b32_e32 v3, v89
	v_lshl_add_u64 v[0:1], v[32:33], 0, v[0:1]
	v_mov_b32_e32 v4, v90
	v_mov_b32_e32 v5, v91
	v_or_b32_e32 v178, 0x70, v178
	v_lshlrev_b32_e32 v8, 16, v2
	v_and_b32_e32 v9, 0xffff0000, v2
	v_lshlrev_b32_e32 v12, 16, v4
	v_and_b32_e32 v4, 0xffff0000, v4
	v_mul_f32_e32 v6, 0xbfb8aa3b, v12
	v_mul_f32_e32 v2, 0xbfb8aa3b, v4
	v_exp_f32_e32 v6, v6
	v_exp_f32_e32 v7, v2
	v_pk_mul_f32 v[8:9], v[10:11], v[8:9]
	v_pk_add_f32 v[6:7], v[6:7], 1.0 op_sel_hi:[1,0]
	s_nop 0
	s_nop 0
	v_rcp_f32_e32 v7, v7
	s_nop 0
	v_mul_f32_e32 v7, v4, v7
	v_mov_b32_e32 v14, 0
	v_rcp_f32_e32 v6, v6
	s_nop 0
	v_mul_f32_e32 v6, v12, v6
	v_pk_mul_f32 v[6:7], v[8:9], v[6:7]
	v_lshlrev_b32_e32 v10, 16, v5
	v_and_b32_e32 v11, 0xffff0000, v5
	v_cvt_pk_bf16_f32 v2, v6, v7
	v_mul_f32_e32 v4, 0xbfb8aa3b, v10
	v_lshlrev_b32_e32 v6, 16, v3
	v_and_b32_e32 v7, 0xffff0000, v3
	v_mul_f32_e32 v3, 0xbfb8aa3b, v11
	v_exp_f32_e32 v4, v4
	v_exp_f32_e32 v5, v3
	v_pk_add_f32 v[8:9], v[34:35], v[26:27] op_sel_hi:[0,1]
	v_pk_mul_f32 v[6:7], v[8:9], v[6:7]
	v_pk_add_f32 v[4:5], v[4:5], 1.0 op_sel_hi:[1,0]
	s_nop 0
	s_nop 0
	v_rcp_f32_e32 v5, v5
	s_nop 0
	v_mul_f32_e32 v5, v11, v5
	v_mov_b32_e32 v13, 0
	v_rcp_f32_e32 v4, v4
	s_nop 0
	v_mul_f32_e32 v4, v10, v4
	v_pk_mul_f32 v[4:5], v[6:7], v[4:5]
	v_pk_add_f32 v[8:9], v[34:35], v[28:29] op_sel_hi:[0,1]
	v_cvt_pk_bf16_f32 v3, v4, v5
	global_store_dwordx2 v[0:1], v[2:3], off
	v_lshl_add_u64 v[0:1], v[38:39], 0, v[178:179]
	v_lshl_add_u64 v[2:3], v[36:37], 0, v[178:179]
	v_mov_b32_e32 v0, v104
	v_mov_b32_e32 v1, v105
	s_nop 0
	v_mov_b32_e32 v2, v106
	v_mov_b32_e32 v3, v107
	v_lshlrev_b32_e32 v6, 16, v0
	v_and_b32_e32 v7, 0xffff0000, v0
	v_lshlrev_b32_e32 v10, 16, v2
	v_and_b32_e32 v2, 0xffff0000, v2
	v_mul_f32_e32 v4, 0xbfb8aa3b, v10
	v_mul_f32_e32 v0, 0xbfb8aa3b, v2
	v_exp_f32_e32 v4, v4
	v_exp_f32_e32 v5, v0
	v_pk_mul_f32 v[6:7], v[8:9], v[6:7]
	v_pk_add_f32 v[4:5], v[4:5], 1.0 op_sel_hi:[1,0]
	s_nop 0
	s_nop 0
	v_rcp_f32_e32 v5, v5
	s_nop 0
	v_mul_f32_e32 v5, v2, v5
	v_mov_b32_e32 v12, 0
	v_rcp_f32_e32 v4, v4
	s_nop 0
	v_mul_f32_e32 v4, v10, v4
	v_pk_mul_f32 v[4:5], v[6:7], v[4:5]
	v_lshlrev_b32_e32 v8, 16, v3
	v_and_b32_e32 v9, 0xffff0000, v3
	v_cvt_pk_bf16_f32 v0, v4, v5
	v_mul_f32_e32 v2, 0xbfb8aa3b, v8
	v_lshlrev_b32_e32 v4, 16, v1
	v_and_b32_e32 v5, 0xffff0000, v1
	v_mul_f32_e32 v1, 0xbfb8aa3b, v9
	v_exp_f32_e32 v2, v2
	v_exp_f32_e32 v3, v1
	v_pk_add_f32 v[6:7], v[34:35], v[30:31] op_sel_hi:[0,1]
	v_pk_mul_f32 v[4:5], v[6:7], v[4:5]
	v_pk_add_f32 v[2:3], v[2:3], 1.0 op_sel_hi:[1,0]
	s_nop 0
	s_nop 0
	v_rcp_f32_e32 v3, v3
	s_nop 0
	v_mul_f32_e32 v3, v9, v3
	s_mov_b64 s[0:1], 0
	v_rcp_f32_e32 v2, v2
	s_nop 0
	v_mul_f32_e32 v2, v8, v2
	v_pk_mul_f32 v[2:3], v[4:5], v[2:3]
	v_mov_b32_e32 v8, 0
	v_cvt_pk_bf16_f32 v1, v2, v3
	v_lshl_add_u64 v[2:3], v[32:33], 0, v[178:179]
	global_store_dwordx2 v[2:3], v[0:1], off
	s_add_u32 s0, s90, s0
	s_addc_u32 s1, s91, s1
	v_add_u32_e32 v0, -16, v92
	v_lshlrev_b32_e32 v122, 3, v121
	v_ashrrev_i32_e32 v1, 5, v121
	s_add_u32 s2, s0, 0x4a50000
	v_and_b32_e32 v123, 0xf8, v122
	v_add_u32_e32 v1, v1, v0
	s_addc_u32 s3, s1, 0
	v_cmp_lt_i32_e32 vcc, -1, v1
	v_lshlrev_b32_e32 v178, 1, v123
	s_and_saveexec_b64 s[4:5], vcc
	s_cbranch_execz .LBB0_447
	v_add_u32_e32 v1, s80, v1
	v_mov_b64_e32 v[2:3], s[2:3]
	v_mad_u64_u32 v[2:3], s[8:9], v1, s33, v[2:3]
	v_lshl_add_u64 v[2:3], v[2:3], 0, v[178:179]
	global_load_dwordx4 v[12:15], v[2:3], off offset:3840
